# speedup vs baseline: 1.0481x; 1.0012x over previous
; template <int EPI> ...
;     ...
;   for (int i = 0; i < nA + nB; ++i) {
;     int pm, pn, koff;
;     bool atom;
;     tile_desc(i, pm, pn, koff, atom);
;     const int kk = atom ? Kc : K;
;     int brow = pm * 256, bcol = pn * 256;
;     void* o = outp;
;     int orow = brow;
;     if (EPI == 0) {
;       if (brow < USPLIT) {
;         o = (void*)p.out;
;       } else {
;         o = (void*)(p.ws + OFF_X);
;         orow = brow - USPLIT;
;       }
;     }
;     if (EPI == 1 && atom) {
;       o = (void*)((float*)(p.ws + OFF_PART) + (long)(koff / Kc) * (256 * DM));
;       orow = 0;
;     }
;     const char* nAb = nullptr;
;     const char* nBb = nullptr;
;     if (i + 1 < nA + nB) {
;       int pm2, pn2, koff2;
;       bool atom2;
;       tile_desc(i + 1, pm2, pn2, koff2, atom2);
;       nAb = (const char*)(A + koff2 + (long)pm2 * 256 * K);
;       nBb = (const char*)(Bt + koff2 + (long)pn2 * 256 * K);
;     }
;     gemm_tile<EPI>(A + koff, Bt + koff, kk, brow, bcol, o, orow, ldo, shm, ss_in, gain_out, atom ? nullptr : nout,
;                    ss_out, K, atom, pre, nAb, nBb);
.LBB0_103:
	s_mul_i32 s2, s59, s1
	s_add_i32 s2, s2, s34
	s_add_i32 s59, s59, 1
	s_cmp_ge_i32 s59, s33
	s_mov_b64 s[88:89], 0
	s_mov_b64 s[92:93], 0
	s_cbranch_scc1 .LBB0_105
	s_add_i32 s6, s2, s1
	s_ashr_i32 s7, s6, 31
	s_lshr_b32 s7, s7, 24
	s_add_i32 s7, s6, s7
	s_ashr_i32 s8, s7, 8
	s_lshl_b32 s8, s8, 3
	s_sub_i32 s9, s0, s8
	s_min_i32 s9, s9, 8
	s_abs_i32 s10, s9
	v_cvt_f32_u32_e32 v0, s10
	s_sub_i32 s20, 0, s10
	s_and_b32 s7, s7, 0xffffff00
	s_sub_i32 s7, s6, s7
	v_rcp_iflag_f32_e32 v0, v0
	s_abs_i32 s6, s7
	s_xor_b32 s11, s7, s9
	s_ashr_i32 s11, s11, 31
	v_mul_f32_e32 v0, 0x4f7ffffe, v0
	v_cvt_u32_f32_e32 v0, v0
	s_nop 0
	v_readfirstlane_b32 s21, v0
	s_mul_i32 s20, s20, s21
	s_mul_hi_u32 s20, s21, s20
	s_add_i32 s21, s21, s20
	s_mul_hi_u32 s20, s6, s21
	s_mul_i32 s21, s20, s10
	s_sub_i32 s6, s6, s21
	s_add_i32 s22, s20, 1
	s_sub_i32 s21, s6, s10
	s_cmp_ge_u32 s6, s10
	s_cselect_b32 s20, s22, s20
	s_cselect_b32 s6, s21, s6
	s_add_i32 s21, s20, 1
	s_cmp_ge_u32 s6, s10
	s_cselect_b32 s6, s21, s20
	s_xor_b32 s6, s6, s11
	s_sub_i32 s6, s6, s11
	s_mul_i32 s9, s6, s9
	s_sub_i32 s7, s7, s9
	s_lshr_b32 s9, s8, 1
	s_and_b32 s9, s9, 28
	s_add_i32 s6, s6, s9
	s_and_b32 s6, s6, 31
	s_add_i32 s8, s7, s8
	s_ashr_i32 s9, s8, 31
	s_lshl_b64 s[8:9], s[8:9], 20
	s_add_u32 s88, s47, s8
	s_addc_u32 s89, s48, s9
	s_ashr_i32 s7, s6, 31
	s_lshl_b64 s[6:7], s[6:7], 20
	s_add_u32 s92, s57, s6
	s_addc_u32 s93, s58, s7
.LBB0_105:
	s_ashr_i32 s6, s2, 31
	s_lshr_b32 s6, s6, 24
	s_add_i32 s6, s2, s6
	s_ashr_i32 s7, s6, 8
	s_lshl_b32 s7, s7, 3
	s_sub_i32 s8, s0, s7
	s_min_i32 s10, s8, 8
	s_abs_i32 s11, s10
	v_cvt_f32_u32_e32 v0, s11
	s_xor_b64 s[8:9], s[12:13], -1
	s_sub_i32 s13, 0, s11
	s_and_b32 s6, s6, 0xffffff00
	v_rcp_iflag_f32_e32 v0, v0
	s_sub_i32 s2, s2, s6
	s_abs_i32 s6, s2
	s_xor_b32 s12, s2, s10
	v_mul_f32_e32 v0, 0x4f7ffffe, v0
	v_cvt_u32_f32_e32 v0, v0
	s_ashr_i32 s12, s12, 31
	v_mov_b32_e32 v134, v193
	v_readfirstlane_b32 s20, v0
	s_mul_i32 s13, s13, s20
	s_mul_hi_u32 s13, s20, s13
	s_add_i32 s20, s20, s13
	s_mul_hi_u32 s13, s6, s20
	s_mul_i32 s20, s13, s11
	s_sub_i32 s6, s6, s20
	s_add_i32 s21, s13, 1
	s_sub_i32 s20, s6, s11
	s_cmp_ge_u32 s6, s11
	s_cselect_b32 s13, s21, s13
	s_cselect_b32 s6, s20, s6
	s_add_i32 s20, s13, 1
	s_cmp_ge_u32 s6, s11
	s_cselect_b32 s6, s20, s13
	s_xor_b32 s6, s6, s12
	s_sub_i32 s6, s6, s12
	s_mul_i32 s10, s6, s10
	s_sub_i32 s2, s2, s10
	s_lshr_b32 s10, s7, 1
	s_and_b32 s10, s10, 28
	s_add_i32 s6, s6, s10
	s_and_b32 s6, s6, 31
	s_add_i32 s7, s7, s2
	s_lshl_b32 s94, s7, 8
	s_lshl_b32 s90, s6, 8
	v_readfirstlane_b32 s2, v134
	s_lshl_b32 s2, s2, 4
	s_ashr_i32 s95, s94, 31
	s_ashr_i32 s91, s90, 31
	s_and_b32 s6, s2, 0x1c00
	s_lshl_b64 s[10:11], s[94:95], 12
	s_lshl_b64 s[12:13], s[90:91], 12
	s_cmp_lg_u32 0, -1
	s_cselect_b32 s2, 0, 0
	v_lshlrev_b32_e32 v2, 4, v134
	v_and_b32_e32 v3, 32, v134
	s_add_i32 s2, s6, s2
	v_lshrrev_b32_e32 v4, 3, v134
	v_bfe_u32 v5, v134, 2, 4
	v_bitop3_b32 v2, v2, v3, 48 bitop3:0x6c
	s_add_u32 s96, s47, s10
	v_and_or_b32 v2, v134, 64, v2
	v_and_or_b32 v3, v4, 48, v5
	s_addc_u32 s97, s48, s11
	v_ashrrev_i32_e32 v0, 8, v134
	v_lshl_or_b32 v132, v3, 12, v2
	s_add_u32 s98, s57, s12
	v_or_b32_e32 v130, 0x40000, v132
	s_addc_u32 s99, s58, s13
	s_mov_b64 s[50:51], -1
	s_andn2_b64 vcc, exec, s[8:9]
	v_cmp_eq_u32_e64 s[12:13], 1, v0
	s_cbranch_vccnz .LBB0_109
	s_cmp_lg_u32 0, -1
	s_cselect_b32 s7, 0, 0
	s_add_i32 s7, s7, s6
	s_add_i32 s20, s7, 0x10000
	s_mov_b32 m0, s20
	s_nop 0
	global_load_lds_dwordx4 v132, s[98:99]
	s_add_i32 s21, s7, 0x12000
	s_mov_b32 m0, s21
	s_nop 0
	global_load_lds_dwordx4 v130, s[98:99]
	s_add_i32 s38, s7, 0x2000
	s_mov_b32 m0, s2
	s_nop 0
	global_load_lds_dwordx4 v132, s[96:97]
	s_add_u32 s8, s98, 0x80000
	s_mov_b32 m0, s38
	s_nop 0
	global_load_lds_dwordx4 v130, s[96:97]
	s_addc_u32 s9, s99, 0
	s_add_i32 s39, s7, 0x14000
	s_mov_b32 m0, s39
	s_nop 0
	global_load_lds_dwordx4 v132, s[8:9]
	s_add_i32 s28, s7, 0x16000
	s_mov_b32 m0, s28
	s_nop 0
	global_load_lds_dwordx4 v130, s[8:9]
	s_add_u32 s8, s96, 0x80000
	s_addc_u32 s9, s97, 0
	s_add_i32 s29, s7, 0x4000
	s_mov_b32 m0, s29
	s_nop 0
	global_load_lds_dwordx4 v132, s[8:9]
	s_add_i32 s62, s7, 0x6000
	s_mov_b32 m0, s62
	s_nop 0
	global_load_lds_dwordx4 v130, s[8:9]
	s_and_saveexec_b64 s[50:51], s[12:13]
	s_cbranch_execz .LBB0_108
	s_barrier
